# P4 finalize: item loop software-pipelined (two loads of item j+4 issued after the store of item j, rotating register sets, 4 copies per trip)
# speedup vs baseline: 1.0058x; 1.0035x over previous
; __device__ __forceinline__ float bf2f(unsigned h) { return __uint_as_float(h << 16); }
; __device__ __forceinline__ unsigned pk2(float lo, float hi) { return f2bf(lo) | (f2bf(hi) << 16); }
; __device__ __forceinline__ float sigmf(float x) { return __builtin_amdgcn_rcpf(1.0f + __expf(-x)); }
; __device__ __forceinline__ void p4_finalize(const Params& p, int G, int bid) {
;     ...
;     for (int it = gw; it < T * 2; it += ngw) { const int tok = it >> 1, h = (it & 1) * 4 + pr;
;         const u32x4 ov = __builtin_nontemporal_load((const u32x4*)(OI + (size_t)tok * D + h * 128 + 8 * l16)); const u32x4 gv = __builtin_nontemporal_load((const u32x4*)(Z + (size_t)tok * ZW + 5120 + h * 128 + 8 * l16));
;         float o[8], gb[8]; float ss = 0.f;
; #pragma unroll
;         for (int c = 0; c < 4; ++c) { o[2 * c] = bf2f(ov[c] & 0xffffu); o[2 * c + 1] = bf2f(ov[c] >> 16); gb[2 * c] = bf2f(gv[c] & 0xffffu); gb[2 * c + 1] = bf2f(gv[c] >> 16); ss += o[2 * c] * o[2 * c] + o[2 * c + 1] * o[2 * c + 1]; }
;         const float rs = rsqrtf(row16_sum_p4(ss) * (1.0f / 128.0f) + 1e-6f);
;         u32x4 w;
; #pragma unroll
;         for (int c = 0; c < 4; ++c) { const float ga = c < 2 ? g0[2 * c] : g1[2 * c - 4], gbq = c < 2 ? g0[2 * c + 1] : g1[2 * c - 3];
;             w[c] = pk2(o[2 * c] * rs * ga * gb[2 * c] * sigmf(gb[2 * c]), o[2 * c + 1] * rs * gbq * gb[2 * c + 1] * sigmf(gb[2 * c + 1])); }
;         *(u32x4*)(Z + (size_t)tok * ZW + 1024 + h * 128 + 8 * l16) = w; }
.LBB0_266:
	s_ashr_i32 s4, s3, 1
	s_ashr_i32 s5, s4, 31
	s_mul_hi_i32 s16, s4, 0x3000
	s_mul_i32 s17, s4, 0x3000
	s_lshl_b64 s[4:5], s[4:5], 11
	v_and_or_b32 v6, s14, 4, v14
	s_add_u32 s4, s11, s4
	v_lshlrev_b32_e32 v8, 8, v6
	s_addc_u32 s5, s12, s5
	v_lshl_add_u64 v[6:7], s[4:5], 0, v[8:9]
	s_add_u32 s4, s7, s17
	v_lshl_add_u64 v[6:7], v[6:7], 0, v[10:11]
	s_addc_u32 s5, s10, s16
	global_load_dwordx4 v[44:47], v[6:7], off nt
	v_lshl_add_u64 v[6:7], s[4:5], 0, v[8:9]
	v_lshl_add_u64 v[6:7], v[6:7], 0, v[10:11]
	v_add_co_u32_e32 v20, vcc, s8, v6
	s_add_i32 s3, s3, s42
	s_nop 0
	v_addc_co_u32_e32 v21, vcc, 0, v7, vcc
	v_mov_b32_e32 v76, v6
	v_mov_b32_e32 v77, v7
	global_load_dwordx4 v[48:51], v[20:21], off offset:2048 nt
	s_add_i32 s14, s14, s13
	s_ashr_i32 s4, s3, 1
	s_ashr_i32 s5, s4, 31
	s_mul_hi_i32 s16, s4, 0x3000
	s_mul_i32 s17, s4, 0x3000
	s_lshl_b64 s[4:5], s[4:5], 11
	v_and_or_b32 v6, s14, 4, v14
	s_add_u32 s4, s11, s4
	v_lshlrev_b32_e32 v8, 8, v6
	s_addc_u32 s5, s12, s5
	v_lshl_add_u64 v[6:7], s[4:5], 0, v[8:9]
	s_add_u32 s4, s7, s17
	v_lshl_add_u64 v[6:7], v[6:7], 0, v[10:11]
	s_addc_u32 s5, s10, s16
	global_load_dwordx4 v[52:55], v[6:7], off nt
	v_lshl_add_u64 v[6:7], s[4:5], 0, v[8:9]
	v_lshl_add_u64 v[6:7], v[6:7], 0, v[10:11]
	v_add_co_u32_e32 v20, vcc, s8, v6
	s_add_i32 s3, s3, s42
	s_nop 0
	v_addc_co_u32_e32 v21, vcc, 0, v7, vcc
	v_mov_b32_e32 v78, v6
	v_mov_b32_e32 v79, v7
	global_load_dwordx4 v[56:59], v[20:21], off offset:2048 nt
	s_add_i32 s14, s14, s13
	s_ashr_i32 s4, s3, 1
	s_ashr_i32 s5, s4, 31
	s_mul_hi_i32 s16, s4, 0x3000
	s_mul_i32 s17, s4, 0x3000
	s_lshl_b64 s[4:5], s[4:5], 11
	v_and_or_b32 v6, s14, 4, v14
	s_add_u32 s4, s11, s4
	v_lshlrev_b32_e32 v8, 8, v6
	s_addc_u32 s5, s12, s5
	v_lshl_add_u64 v[6:7], s[4:5], 0, v[8:9]
	s_add_u32 s4, s7, s17
	v_lshl_add_u64 v[6:7], v[6:7], 0, v[10:11]
	s_addc_u32 s5, s10, s16
	global_load_dwordx4 v[60:63], v[6:7], off nt
	v_lshl_add_u64 v[6:7], s[4:5], 0, v[8:9]
	v_lshl_add_u64 v[6:7], v[6:7], 0, v[10:11]
	v_add_co_u32_e32 v20, vcc, s8, v6
	s_add_i32 s3, s3, s42
	s_nop 0
	v_addc_co_u32_e32 v21, vcc, 0, v7, vcc
	v_mov_b32_e32 v80, v6
	v_mov_b32_e32 v81, v7
	global_load_dwordx4 v[64:67], v[20:21], off offset:2048 nt
	s_add_i32 s14, s14, s13
	s_ashr_i32 s4, s3, 1
	s_ashr_i32 s5, s4, 31
	s_mul_hi_i32 s16, s4, 0x3000
	s_mul_i32 s17, s4, 0x3000
	s_lshl_b64 s[4:5], s[4:5], 11
	v_and_or_b32 v6, s14, 4, v14
	s_add_u32 s4, s11, s4
	v_lshlrev_b32_e32 v8, 8, v6
	s_addc_u32 s5, s12, s5
	v_lshl_add_u64 v[6:7], s[4:5], 0, v[8:9]
	s_add_u32 s4, s7, s17
	v_lshl_add_u64 v[6:7], v[6:7], 0, v[10:11]
	s_addc_u32 s5, s10, s16
	global_load_dwordx4 v[68:71], v[6:7], off nt
	v_lshl_add_u64 v[6:7], s[4:5], 0, v[8:9]
	v_lshl_add_u64 v[6:7], v[6:7], 0, v[10:11]
	v_add_co_u32_e32 v20, vcc, s8, v6
	s_add_i32 s3, s3, s42
	s_nop 0
	v_addc_co_u32_e32 v21, vcc, 0, v7, vcc
	v_mov_b32_e32 v82, v6
	v_mov_b32_e32 v83, v7
	global_load_dwordx4 v[72:75], v[20:21], off offset:2048 nt
	s_add_i32 s14, s14, s13
	s_mov_b32 s98, 0
.Lp4_trip:
	s_waitcnt vmcnt(6)
	v_mov_b32_e32 v16, v44
	v_mov_b32_e32 v17, v45
	v_mov_b32_e32 v18, v46
	v_mov_b32_e32 v19, v47
	v_mov_b32_e32 v20, v48
	v_mov_b32_e32 v21, v49
	v_mov_b32_e32 v22, v50
	v_mov_b32_e32 v23, v51
	v_mov_b32_e32 v6, v76
	v_mov_b32_e32 v7, v77
	v_lshlrev_b32_e32 v25, 16, v17
	v_lshlrev_b32_e32 v24, 16, v16
	v_and_b32_e32 v17, 0xffff0000, v17
	v_and_b32_e32 v16, 0xffff0000, v16
	v_lshlrev_b32_e32 v27, 16, v19
	v_lshlrev_b32_e32 v26, 16, v18
	v_pk_mul_f32 v[28:29], v[24:25], v[24:25]
	v_and_b32_e32 v19, 0xffff0000, v19
	v_and_b32_e32 v18, 0xffff0000, v18
	v_pk_mul_f32 v[30:31], v[26:27], v[26:27]
	v_pk_fma_f32 v[28:29], v[16:17], v[16:17], v[28:29]
	v_pk_fma_f32 v[30:31], v[18:19], v[18:19], v[30:31]
	v_add_f32_e32 v8, v28, v29
	v_lshlrev_b32_e32 v33, 16, v21
	v_lshlrev_b32_e32 v32, 16, v20
	v_and_b32_e32 v20, 0xffff0000, v20
	v_lshlrev_b32_e32 v34, 16, v22
	v_add_f32_e32 v8, v30, v8
	v_mul_f32_e32 v29, 0xbfb8aa3b, v20
	v_mul_f32_e32 v36, 0xbfb8aa3b, v33
	v_mul_f32_e32 v30, 0xbfb8aa3b, v34
	v_add_f32_e32 v8, v31, v8
	v_exp_f32_e32 v29, v29
	v_exp_f32_e32 v36, v36
	v_exp_f32_e32 v30, v30
	v_add_f32_dpp v8, v8, v8 quad_perm:[1,0,3,2] row_mask:0xf bank_mask:0xf bound_ctrl:1
	v_lshlrev_b32_e32 v35, 16, v23
	v_and_b32_e32 v23, 0xffff0000, v23
	v_add_f32_dpp v8, v8, v8 quad_perm:[2,3,0,1] row_mask:0xf bank_mask:0xf bound_ctrl:1
	v_and_b32_e32 v22, 0xffff0000, v22
	v_mul_f32_e32 v38, 0xbfb8aa3b, v22
	v_add_f32_dpp v8, v8, v8 row_half_mirror row_mask:0xf bank_mask:0xf bound_ctrl:1
	v_mul_f32_e32 v39, 0xbfb8aa3b, v35
	v_mul_f32_e32 v40, 0xbfb8aa3b, v23
	v_add_f32_dpp v8, v8, v8 row_mirror row_mask:0xf bank_mask:0xf bound_ctrl:1
	v_exp_f32_e32 v31, v38
	v_exp_f32_e32 v38, v39
	v_exp_f32_e32 v39, v40
	v_add_f32_e32 v29, 1.0, v29
	v_add_f32_e32 v36, 1.0, v36
	v_add_f32_e32 v40, 1.0, v30
	v_fmamk_f32 v8, v8, 0x3c000000, v15
	v_and_b32_e32 v21, 0xffff0000, v21
	v_rcp_f32_e32 v30, v29
	v_rcp_f32_e32 v29, v36
	v_rcp_f32_e32 v36, v40
	v_mul_f32_e32 v40, 0x4b800000, v8
	v_cmp_gt_f32_e32 vcc, s15, v8
	v_mul_f32_e32 v28, 0xbfb8aa3b, v32
	v_mul_f32_e32 v37, 0xbfb8aa3b, v21
	v_cndmask_b32_e32 v8, v8, v40, vcc
	v_exp_f32_e32 v28, v28
	v_exp_f32_e32 v37, v37
	v_rsq_f32_e32 v8, v8
	v_add_f32_e32 v41, 1.0, v31
	v_add_f32_e32 v28, 1.0, v28
	v_add_f32_e32 v37, 1.0, v37
	v_add_f32_e32 v42, 1.0, v38
	v_add_f32_e32 v39, 1.0, v39
	v_mul_f32_e32 v40, 0x45800000, v8
	v_rcp_f32_e32 v28, v28
	v_rcp_f32_e32 v31, v37
	v_rcp_f32_e32 v38, v41
	v_rcp_f32_e32 v37, v42
	v_rcp_f32_e32 v39, v39
	v_cndmask_b32_e32 v8, v8, v40, vcc
	v_pk_mul_f32 v[24:25], v[8:9], v[24:25] op_sel_hi:[0,1]
; __device__ __forceinline__ float bf2f(unsigned h) { return __uint_as_float(h << 16); }
; __device__ __forceinline__ unsigned pk2(float lo, float hi) { return f2bf(lo) | (f2bf(hi) << 16); }
; __device__ __forceinline__ float sigmf(float x) { return __builtin_amdgcn_rcpf(1.0f + __expf(-x)); }
; __device__ __forceinline__ void p4_finalize(const Params& p, int G, int bid) {
;     ...
;     for (int it = gw; it < T * 2; it += ngw) { const int tok = it >> 1, h = (it & 1) * 4 + pr;
;         const u32x4 ov = __builtin_nontemporal_load((const u32x4*)(OI + (size_t)tok * D + h * 128 + 8 * l16)); const u32x4 gv = __builtin_nontemporal_load((const u32x4*)(Z + (size_t)tok * ZW + 5120 + h * 128 + 8 * l16));
;         float o[8], gb[8]; float ss = 0.f;
; #pragma unroll
;         for (int c = 0; c < 4; ++c) { o[2 * c] = bf2f(ov[c] & 0xffffu); o[2 * c + 1] = bf2f(ov[c] >> 16); gb[2 * c] = bf2f(gv[c] & 0xffffu); gb[2 * c + 1] = bf2f(gv[c] >> 16); ss += o[2 * c] * o[2 * c] + o[2 * c + 1] * o[2 * c + 1]; }
;         const float rs = rsqrtf(row16_sum_p4(ss) * (1.0f / 128.0f) + 1e-6f);
;         u32x4 w;
; #pragma unroll
;         for (int c = 0; c < 4; ++c) { const float ga = c < 2 ? g0[2 * c] : g1[2 * c - 4], gbq = c < 2 ? g0[2 * c + 1] : g1[2 * c - 3];
;             w[c] = pk2(o[2 * c] * rs * ga * gb[2 * c] * sigmf(gb[2 * c]), o[2 * c + 1] * rs * gbq * gb[2 * c + 1] * sigmf(gb[2 * c + 1])); }
;         *(u32x4*)(Z + (size_t)tok * ZW + 1024 + h * 128 + 8 * l16) = w; }
	v_pk_mul_f32 v[16:17], v[8:9], v[16:17] op_sel_hi:[0,1]
	v_pk_mul_f32 v[26:27], v[8:9], v[26:27] op_sel_hi:[0,1]
	v_pk_mul_f32 v[18:19], v[8:9], v[18:19] op_sel_hi:[0,1]
	v_pk_mul_f32 v[24:25], v[0:1], v[24:25]
	v_pk_mul_f32 v[16:17], v[12:13], v[16:17]
	v_pk_mul_f32 v[26:27], v[4:5], v[26:27]
	v_pk_mul_f32 v[18:19], v[2:3], v[18:19]
	v_pk_mul_f32 v[24:25], v[24:25], v[32:33]
	v_pk_mul_f32 v[16:17], v[16:17], v[20:21]
	v_pk_mul_f32 v[20:21], v[26:27], v[34:35]
	v_pk_mul_f32 v[18:19], v[18:19], v[22:23]
	v_pk_mul_f32 v[22:23], v[28:29], v[24:25]
	v_pk_mul_f32 v[20:21], v[36:37], v[20:21]
	v_pk_mul_f32 v[18:19], v[38:39], v[18:19]
	v_pk_mul_f32 v[16:17], v[30:31], v[16:17]
	v_bfe_u32 v8, v19, 16, 1
	v_bfe_u32 v27, v22, 16, 1
	v_bfe_u32 v28, v23, 16, 1
	v_bfe_u32 v29, v20, 16, 1
	v_bfe_u32 v30, v21, 16, 1
	v_bfe_u32 v24, v18, 16, 1
	v_bfe_u32 v25, v17, 16, 1
	v_bfe_u32 v26, v16, 16, 1
	v_add3_u32 v8, v19, v8, s6
	v_add3_u32 v19, v21, v30, s6
	v_add3_u32 v20, v20, v29, s6
	v_add3_u32 v21, v23, v28, s6
	v_add3_u32 v22, v22, v27, s6
	v_add3_u32 v16, v16, v26, s6
	v_add3_u32 v17, v17, v25, s6
	v_add3_u32 v18, v18, v24, s6
	v_lshrrev_b32_e32 v22, 16, v22
	v_lshrrev_b32_e32 v21, 16, v21
	v_lshrrev_b32_e32 v20, 16, v20
	v_lshrrev_b32_e32 v19, 16, v19
	v_and_or_b32 v19, v8, s9, v19
	v_and_or_b32 v18, v18, s9, v20
	v_and_or_b32 v17, v17, s9, v21
	v_and_or_b32 v16, v16, s9, v22
	global_store_dwordx4 v[6:7], v[16:19], off offset:2048
	s_ashr_i32 s4, s3, 1
	s_ashr_i32 s5, s4, 31
	s_mul_hi_i32 s16, s4, 0x3000
	s_mul_i32 s17, s4, 0x3000
	s_lshl_b64 s[4:5], s[4:5], 11
	v_and_or_b32 v6, s14, 4, v14
	s_add_u32 s4, s11, s4
	v_lshlrev_b32_e32 v8, 8, v6
	s_addc_u32 s5, s12, s5
	v_lshl_add_u64 v[6:7], s[4:5], 0, v[8:9]
	s_add_u32 s4, s7, s17
	v_lshl_add_u64 v[6:7], v[6:7], 0, v[10:11]
	s_addc_u32 s5, s10, s16
	global_load_dwordx4 v[44:47], v[6:7], off nt
	v_lshl_add_u64 v[6:7], s[4:5], 0, v[8:9]
	v_lshl_add_u64 v[6:7], v[6:7], 0, v[10:11]
	v_add_co_u32_e32 v20, vcc, s8, v6
	s_add_i32 s3, s3, s42
	s_nop 0
	v_addc_co_u32_e32 v21, vcc, 0, v7, vcc
	v_mov_b32_e32 v76, v6
	v_mov_b32_e32 v77, v7
	global_load_dwordx4 v[48:51], v[20:21], off offset:2048 nt
	s_add_i32 s14, s14, s13
	s_waitcnt vmcnt(7)
	v_mov_b32_e32 v16, v52
	v_mov_b32_e32 v17, v53
	v_mov_b32_e32 v18, v54
	v_mov_b32_e32 v19, v55
	v_mov_b32_e32 v20, v56
	v_mov_b32_e32 v21, v57
	v_mov_b32_e32 v22, v58
	v_mov_b32_e32 v23, v59
	v_mov_b32_e32 v6, v78
	v_mov_b32_e32 v7, v79
	v_lshlrev_b32_e32 v25, 16, v17
	v_lshlrev_b32_e32 v24, 16, v16
	v_and_b32_e32 v17, 0xffff0000, v17
	v_and_b32_e32 v16, 0xffff0000, v16
	v_lshlrev_b32_e32 v27, 16, v19
	v_lshlrev_b32_e32 v26, 16, v18
	v_pk_mul_f32 v[28:29], v[24:25], v[24:25]
	v_and_b32_e32 v19, 0xffff0000, v19
	v_and_b32_e32 v18, 0xffff0000, v18
	v_pk_mul_f32 v[30:31], v[26:27], v[26:27]
	v_pk_fma_f32 v[28:29], v[16:17], v[16:17], v[28:29]
	v_pk_fma_f32 v[30:31], v[18:19], v[18:19], v[30:31]
	v_add_f32_e32 v8, v28, v29
	v_lshlrev_b32_e32 v33, 16, v21
	v_lshlrev_b32_e32 v32, 16, v20
	v_and_b32_e32 v20, 0xffff0000, v20
	v_lshlrev_b32_e32 v34, 16, v22
	v_add_f32_e32 v8, v30, v8
	v_mul_f32_e32 v29, 0xbfb8aa3b, v20
	v_mul_f32_e32 v36, 0xbfb8aa3b, v33
	v_mul_f32_e32 v30, 0xbfb8aa3b, v34
	v_add_f32_e32 v8, v31, v8
	v_exp_f32_e32 v29, v29
	v_exp_f32_e32 v36, v36
	v_exp_f32_e32 v30, v30
	v_add_f32_dpp v8, v8, v8 quad_perm:[1,0,3,2] row_mask:0xf bank_mask:0xf bound_ctrl:1
	v_lshlrev_b32_e32 v35, 16, v23
	v_and_b32_e32 v23, 0xffff0000, v23
	v_add_f32_dpp v8, v8, v8 quad_perm:[2,3,0,1] row_mask:0xf bank_mask:0xf bound_ctrl:1
	v_and_b32_e32 v22, 0xffff0000, v22
	v_mul_f32_e32 v38, 0xbfb8aa3b, v22
	v_add_f32_dpp v8, v8, v8 row_half_mirror row_mask:0xf bank_mask:0xf bound_ctrl:1
	v_mul_f32_e32 v39, 0xbfb8aa3b, v35
	v_mul_f32_e32 v40, 0xbfb8aa3b, v23
	v_add_f32_dpp v8, v8, v8 row_mirror row_mask:0xf bank_mask:0xf bound_ctrl:1
	v_exp_f32_e32 v31, v38
	v_exp_f32_e32 v38, v39
	v_exp_f32_e32 v39, v40
	v_add_f32_e32 v29, 1.0, v29
	v_add_f32_e32 v36, 1.0, v36
	v_add_f32_e32 v40, 1.0, v30
	v_fmamk_f32 v8, v8, 0x3c000000, v15
	v_and_b32_e32 v21, 0xffff0000, v21
	v_rcp_f32_e32 v30, v29
	v_rcp_f32_e32 v29, v36
	v_rcp_f32_e32 v36, v40
	v_mul_f32_e32 v40, 0x4b800000, v8
	v_cmp_gt_f32_e32 vcc, s15, v8
	v_mul_f32_e32 v28, 0xbfb8aa3b, v32
	v_mul_f32_e32 v37, 0xbfb8aa3b, v21
	v_cndmask_b32_e32 v8, v8, v40, vcc
	v_exp_f32_e32 v28, v28
	v_exp_f32_e32 v37, v37
	v_rsq_f32_e32 v8, v8
	v_add_f32_e32 v41, 1.0, v31
	v_add_f32_e32 v28, 1.0, v28
	v_add_f32_e32 v37, 1.0, v37
	v_add_f32_e32 v42, 1.0, v38
	v_add_f32_e32 v39, 1.0, v39
	v_mul_f32_e32 v40, 0x45800000, v8
	v_rcp_f32_e32 v28, v28
	v_rcp_f32_e32 v31, v37
	v_rcp_f32_e32 v38, v41
	v_rcp_f32_e32 v37, v42
	v_rcp_f32_e32 v39, v39
	v_cndmask_b32_e32 v8, v8, v40, vcc
	v_pk_mul_f32 v[24:25], v[8:9], v[24:25] op_sel_hi:[0,1]
	v_pk_mul_f32 v[16:17], v[8:9], v[16:17] op_sel_hi:[0,1]
	v_pk_mul_f32 v[26:27], v[8:9], v[26:27] op_sel_hi:[0,1]
	v_pk_mul_f32 v[18:19], v[8:9], v[18:19] op_sel_hi:[0,1]
	v_pk_mul_f32 v[24:25], v[0:1], v[24:25]
	v_pk_mul_f32 v[16:17], v[12:13], v[16:17]
	v_pk_mul_f32 v[26:27], v[4:5], v[26:27]
	v_pk_mul_f32 v[18:19], v[2:3], v[18:19]
	v_pk_mul_f32 v[24:25], v[24:25], v[32:33]
	v_pk_mul_f32 v[16:17], v[16:17], v[20:21]
	v_pk_mul_f32 v[20:21], v[26:27], v[34:35]
	v_pk_mul_f32 v[18:19], v[18:19], v[22:23]
	v_pk_mul_f32 v[22:23], v[28:29], v[24:25]
	v_pk_mul_f32 v[20:21], v[36:37], v[20:21]
	v_pk_mul_f32 v[18:19], v[38:39], v[18:19]
	v_pk_mul_f32 v[16:17], v[30:31], v[16:17]
	v_bfe_u32 v8, v19, 16, 1
	v_bfe_u32 v27, v22, 16, 1
	v_bfe_u32 v28, v23, 16, 1
	v_bfe_u32 v29, v20, 16, 1
	v_bfe_u32 v30, v21, 16, 1
	v_bfe_u32 v24, v18, 16, 1
	v_bfe_u32 v25, v17, 16, 1
	v_bfe_u32 v26, v16, 16, 1
	v_add3_u32 v8, v19, v8, s6
	v_add3_u32 v19, v21, v30, s6
	v_add3_u32 v20, v20, v29, s6
	v_add3_u32 v21, v23, v28, s6
	v_add3_u32 v22, v22, v27, s6
	v_add3_u32 v16, v16, v26, s6
	v_add3_u32 v17, v17, v25, s6
	v_add3_u32 v18, v18, v24, s6
	v_lshrrev_b32_e32 v22, 16, v22
	v_lshrrev_b32_e32 v21, 16, v21
	v_lshrrev_b32_e32 v20, 16, v20
	v_lshrrev_b32_e32 v19, 16, v19
	v_and_or_b32 v19, v8, s9, v19
	v_and_or_b32 v18, v18, s9, v20
	v_and_or_b32 v17, v17, s9, v21
	v_and_or_b32 v16, v16, s9, v22
	global_store_dwordx4 v[6:7], v[16:19], off offset:2048
	s_ashr_i32 s4, s3, 1
	s_ashr_i32 s5, s4, 31
	s_mul_hi_i32 s16, s4, 0x3000
	s_mul_i32 s17, s4, 0x3000
	s_lshl_b64 s[4:5], s[4:5], 11
	v_and_or_b32 v6, s14, 4, v14
	s_add_u32 s4, s11, s4
	v_lshlrev_b32_e32 v8, 8, v6
	s_addc_u32 s5, s12, s5
	v_lshl_add_u64 v[6:7], s[4:5], 0, v[8:9]
	s_add_u32 s4, s7, s17
	v_lshl_add_u64 v[6:7], v[6:7], 0, v[10:11]
	s_addc_u32 s5, s10, s16
	global_load_dwordx4 v[52:55], v[6:7], off nt
	v_lshl_add_u64 v[6:7], s[4:5], 0, v[8:9]
	v_lshl_add_u64 v[6:7], v[6:7], 0, v[10:11]
	v_add_co_u32_e32 v20, vcc, s8, v6
	s_add_i32 s3, s3, s42
	s_nop 0
	v_addc_co_u32_e32 v21, vcc, 0, v7, vcc
	v_mov_b32_e32 v78, v6
	v_mov_b32_e32 v79, v7
	global_load_dwordx4 v[56:59], v[20:21], off offset:2048 nt
	s_add_i32 s14, s14, s13
	s_waitcnt vmcnt(8)
; __device__ __forceinline__ float bf2f(unsigned h) { return __uint_as_float(h << 16); }
; __device__ __forceinline__ unsigned pk2(float lo, float hi) { return f2bf(lo) | (f2bf(hi) << 16); }
; __device__ __forceinline__ float sigmf(float x) { return __builtin_amdgcn_rcpf(1.0f + __expf(-x)); }
; __device__ __forceinline__ void p4_finalize(const Params& p, int G, int bid) {
;     ...
;     for (int it = gw; it < T * 2; it += ngw) { const int tok = it >> 1, h = (it & 1) * 4 + pr;
;         const u32x4 ov = __builtin_nontemporal_load((const u32x4*)(OI + (size_t)tok * D + h * 128 + 8 * l16)); const u32x4 gv = __builtin_nontemporal_load((const u32x4*)(Z + (size_t)tok * ZW + 5120 + h * 128 + 8 * l16));
;         float o[8], gb[8]; float ss = 0.f;
; #pragma unroll
;         for (int c = 0; c < 4; ++c) { o[2 * c] = bf2f(ov[c] & 0xffffu); o[2 * c + 1] = bf2f(ov[c] >> 16); gb[2 * c] = bf2f(gv[c] & 0xffffu); gb[2 * c + 1] = bf2f(gv[c] >> 16); ss += o[2 * c] * o[2 * c] + o[2 * c + 1] * o[2 * c + 1]; }
;         const float rs = rsqrtf(row16_sum_p4(ss) * (1.0f / 128.0f) + 1e-6f);
;         u32x4 w;
; #pragma unroll
;         for (int c = 0; c < 4; ++c) { const float ga = c < 2 ? g0[2 * c] : g1[2 * c - 4], gbq = c < 2 ? g0[2 * c + 1] : g1[2 * c - 3];
;             w[c] = pk2(o[2 * c] * rs * ga * gb[2 * c] * sigmf(gb[2 * c]), o[2 * c + 1] * rs * gbq * gb[2 * c + 1] * sigmf(gb[2 * c + 1])); }
;         *(u32x4*)(Z + (size_t)tok * ZW + 1024 + h * 128 + 8 * l16) = w; }
	v_mov_b32_e32 v16, v60
	v_mov_b32_e32 v17, v61
	v_mov_b32_e32 v18, v62
	v_mov_b32_e32 v19, v63
	v_mov_b32_e32 v20, v64
	v_mov_b32_e32 v21, v65
	v_mov_b32_e32 v22, v66
	v_mov_b32_e32 v23, v67
	v_mov_b32_e32 v6, v80
	v_mov_b32_e32 v7, v81
	v_lshlrev_b32_e32 v25, 16, v17
	v_lshlrev_b32_e32 v24, 16, v16
	v_and_b32_e32 v17, 0xffff0000, v17
	v_and_b32_e32 v16, 0xffff0000, v16
	v_lshlrev_b32_e32 v27, 16, v19
	v_lshlrev_b32_e32 v26, 16, v18
	v_pk_mul_f32 v[28:29], v[24:25], v[24:25]
	v_and_b32_e32 v19, 0xffff0000, v19
	v_and_b32_e32 v18, 0xffff0000, v18
	v_pk_mul_f32 v[30:31], v[26:27], v[26:27]
	v_pk_fma_f32 v[28:29], v[16:17], v[16:17], v[28:29]
	v_pk_fma_f32 v[30:31], v[18:19], v[18:19], v[30:31]
	v_add_f32_e32 v8, v28, v29
	v_lshlrev_b32_e32 v33, 16, v21
	v_lshlrev_b32_e32 v32, 16, v20
	v_and_b32_e32 v20, 0xffff0000, v20
	v_lshlrev_b32_e32 v34, 16, v22
	v_add_f32_e32 v8, v30, v8
	v_mul_f32_e32 v29, 0xbfb8aa3b, v20
	v_mul_f32_e32 v36, 0xbfb8aa3b, v33
	v_mul_f32_e32 v30, 0xbfb8aa3b, v34
	v_add_f32_e32 v8, v31, v8
	v_exp_f32_e32 v29, v29
	v_exp_f32_e32 v36, v36
	v_exp_f32_e32 v30, v30
	v_add_f32_dpp v8, v8, v8 quad_perm:[1,0,3,2] row_mask:0xf bank_mask:0xf bound_ctrl:1
	v_lshlrev_b32_e32 v35, 16, v23
	v_and_b32_e32 v23, 0xffff0000, v23
	v_add_f32_dpp v8, v8, v8 quad_perm:[2,3,0,1] row_mask:0xf bank_mask:0xf bound_ctrl:1
	v_and_b32_e32 v22, 0xffff0000, v22
	v_mul_f32_e32 v38, 0xbfb8aa3b, v22
	v_add_f32_dpp v8, v8, v8 row_half_mirror row_mask:0xf bank_mask:0xf bound_ctrl:1
	v_mul_f32_e32 v39, 0xbfb8aa3b, v35
	v_mul_f32_e32 v40, 0xbfb8aa3b, v23
	v_add_f32_dpp v8, v8, v8 row_mirror row_mask:0xf bank_mask:0xf bound_ctrl:1
	v_exp_f32_e32 v31, v38
	v_exp_f32_e32 v38, v39
	v_exp_f32_e32 v39, v40
	v_add_f32_e32 v29, 1.0, v29
	v_add_f32_e32 v36, 1.0, v36
	v_add_f32_e32 v40, 1.0, v30
	v_fmamk_f32 v8, v8, 0x3c000000, v15
	v_and_b32_e32 v21, 0xffff0000, v21
	v_rcp_f32_e32 v30, v29
	v_rcp_f32_e32 v29, v36
	v_rcp_f32_e32 v36, v40
	v_mul_f32_e32 v40, 0x4b800000, v8
	v_cmp_gt_f32_e32 vcc, s15, v8
	v_mul_f32_e32 v28, 0xbfb8aa3b, v32
	v_mul_f32_e32 v37, 0xbfb8aa3b, v21
	v_cndmask_b32_e32 v8, v8, v40, vcc
	v_exp_f32_e32 v28, v28
	v_exp_f32_e32 v37, v37
	v_rsq_f32_e32 v8, v8
	v_add_f32_e32 v41, 1.0, v31
	v_add_f32_e32 v28, 1.0, v28
	v_add_f32_e32 v37, 1.0, v37
	v_add_f32_e32 v42, 1.0, v38
	v_add_f32_e32 v39, 1.0, v39
	v_mul_f32_e32 v40, 0x45800000, v8
	v_rcp_f32_e32 v28, v28
	v_rcp_f32_e32 v31, v37
	v_rcp_f32_e32 v38, v41
	v_rcp_f32_e32 v37, v42
	v_rcp_f32_e32 v39, v39
	v_cndmask_b32_e32 v8, v8, v40, vcc
	v_pk_mul_f32 v[24:25], v[8:9], v[24:25] op_sel_hi:[0,1]
	v_pk_mul_f32 v[16:17], v[8:9], v[16:17] op_sel_hi:[0,1]
	v_pk_mul_f32 v[26:27], v[8:9], v[26:27] op_sel_hi:[0,1]
	v_pk_mul_f32 v[18:19], v[8:9], v[18:19] op_sel_hi:[0,1]
	v_pk_mul_f32 v[24:25], v[0:1], v[24:25]
	v_pk_mul_f32 v[16:17], v[12:13], v[16:17]
	v_pk_mul_f32 v[26:27], v[4:5], v[26:27]
	v_pk_mul_f32 v[18:19], v[2:3], v[18:19]
	v_pk_mul_f32 v[24:25], v[24:25], v[32:33]
	v_pk_mul_f32 v[16:17], v[16:17], v[20:21]
	v_pk_mul_f32 v[20:21], v[26:27], v[34:35]
	v_pk_mul_f32 v[18:19], v[18:19], v[22:23]
	v_pk_mul_f32 v[22:23], v[28:29], v[24:25]
	v_pk_mul_f32 v[20:21], v[36:37], v[20:21]
	v_pk_mul_f32 v[18:19], v[38:39], v[18:19]
	v_pk_mul_f32 v[16:17], v[30:31], v[16:17]
	v_bfe_u32 v8, v19, 16, 1
	v_bfe_u32 v27, v22, 16, 1
	v_bfe_u32 v28, v23, 16, 1
	v_bfe_u32 v29, v20, 16, 1
	v_bfe_u32 v30, v21, 16, 1
	v_bfe_u32 v24, v18, 16, 1
	v_bfe_u32 v25, v17, 16, 1
	v_bfe_u32 v26, v16, 16, 1
	v_add3_u32 v8, v19, v8, s6
	v_add3_u32 v19, v21, v30, s6
	v_add3_u32 v20, v20, v29, s6
	v_add3_u32 v21, v23, v28, s6
	v_add3_u32 v22, v22, v27, s6
	v_add3_u32 v16, v16, v26, s6
	v_add3_u32 v17, v17, v25, s6
	v_add3_u32 v18, v18, v24, s6
	v_lshrrev_b32_e32 v22, 16, v22
	v_lshrrev_b32_e32 v21, 16, v21
	v_lshrrev_b32_e32 v20, 16, v20
	v_lshrrev_b32_e32 v19, 16, v19
	v_and_or_b32 v19, v8, s9, v19
	v_and_or_b32 v18, v18, s9, v20
	v_and_or_b32 v17, v17, s9, v21
	v_and_or_b32 v16, v16, s9, v22
	global_store_dwordx4 v[6:7], v[16:19], off offset:2048
	s_ashr_i32 s4, s3, 1
	s_ashr_i32 s5, s4, 31
	s_mul_hi_i32 s16, s4, 0x3000
	s_mul_i32 s17, s4, 0x3000
	s_lshl_b64 s[4:5], s[4:5], 11
	v_and_or_b32 v6, s14, 4, v14
	s_add_u32 s4, s11, s4
	v_lshlrev_b32_e32 v8, 8, v6
	s_addc_u32 s5, s12, s5
	v_lshl_add_u64 v[6:7], s[4:5], 0, v[8:9]
	s_add_u32 s4, s7, s17
	v_lshl_add_u64 v[6:7], v[6:7], 0, v[10:11]
	s_addc_u32 s5, s10, s16
	global_load_dwordx4 v[60:63], v[6:7], off nt
	v_lshl_add_u64 v[6:7], s[4:5], 0, v[8:9]
	v_lshl_add_u64 v[6:7], v[6:7], 0, v[10:11]
	v_add_co_u32_e32 v20, vcc, s8, v6
	s_add_i32 s3, s3, s42
	s_nop 0
	v_addc_co_u32_e32 v21, vcc, 0, v7, vcc
	v_mov_b32_e32 v80, v6
	v_mov_b32_e32 v81, v7
	global_load_dwordx4 v[64:67], v[20:21], off offset:2048 nt
	s_add_i32 s14, s14, s13
	s_waitcnt vmcnt(9)
; __device__ __forceinline__ float bf2f(unsigned h) { return __uint_as_float(h << 16); }
; __device__ __forceinline__ unsigned pk2(float lo, float hi) { return f2bf(lo) | (f2bf(hi) << 16); }
; __device__ __forceinline__ float sigmf(float x) { return __builtin_amdgcn_rcpf(1.0f + __expf(-x)); }
; __device__ __forceinline__ void p4_finalize(const Params& p, int G, int bid) {
;     ...
;     for (int it = gw; it < T * 2; it += ngw) { const int tok = it >> 1, h = (it & 1) * 4 + pr;
;         const u32x4 ov = __builtin_nontemporal_load((const u32x4*)(OI + (size_t)tok * D + h * 128 + 8 * l16)); const u32x4 gv = __builtin_nontemporal_load((const u32x4*)(Z + (size_t)tok * ZW + 5120 + h * 128 + 8 * l16));
;         float o[8], gb[8]; float ss = 0.f;
; #pragma unroll
;         for (int c = 0; c < 4; ++c) { o[2 * c] = bf2f(ov[c] & 0xffffu); o[2 * c + 1] = bf2f(ov[c] >> 16); gb[2 * c] = bf2f(gv[c] & 0xffffu); gb[2 * c + 1] = bf2f(gv[c] >> 16); ss += o[2 * c] * o[2 * c] + o[2 * c + 1] * o[2 * c + 1]; }
;         const float rs = rsqrtf(row16_sum_p4(ss) * (1.0f / 128.0f) + 1e-6f);
;         u32x4 w;
; #pragma unroll
;         for (int c = 0; c < 4; ++c) { const float ga = c < 2 ? g0[2 * c] : g1[2 * c - 4], gbq = c < 2 ? g0[2 * c + 1] : g1[2 * c - 3];
;             w[c] = pk2(o[2 * c] * rs * ga * gb[2 * c] * sigmf(gb[2 * c]), o[2 * c + 1] * rs * gbq * gb[2 * c + 1] * sigmf(gb[2 * c + 1])); }
;         *(u32x4*)(Z + (size_t)tok * ZW + 1024 + h * 128 + 8 * l16) = w; }
	v_mov_b32_e32 v16, v68
	v_mov_b32_e32 v17, v69
	v_mov_b32_e32 v18, v70
	v_mov_b32_e32 v19, v71
	v_mov_b32_e32 v20, v72
	v_mov_b32_e32 v21, v73
	v_mov_b32_e32 v22, v74
	v_mov_b32_e32 v23, v75
	v_mov_b32_e32 v6, v82
	v_mov_b32_e32 v7, v83
	v_lshlrev_b32_e32 v25, 16, v17
	v_lshlrev_b32_e32 v24, 16, v16
	v_and_b32_e32 v17, 0xffff0000, v17
	v_and_b32_e32 v16, 0xffff0000, v16
	v_lshlrev_b32_e32 v27, 16, v19
	v_lshlrev_b32_e32 v26, 16, v18
	v_pk_mul_f32 v[28:29], v[24:25], v[24:25]
	v_and_b32_e32 v19, 0xffff0000, v19
	v_and_b32_e32 v18, 0xffff0000, v18
	v_pk_mul_f32 v[30:31], v[26:27], v[26:27]
	v_pk_fma_f32 v[28:29], v[16:17], v[16:17], v[28:29]
	v_pk_fma_f32 v[30:31], v[18:19], v[18:19], v[30:31]
	v_add_f32_e32 v8, v28, v29
	v_lshlrev_b32_e32 v33, 16, v21
	v_lshlrev_b32_e32 v32, 16, v20
	v_and_b32_e32 v20, 0xffff0000, v20
	v_lshlrev_b32_e32 v34, 16, v22
	v_add_f32_e32 v8, v30, v8
	v_mul_f32_e32 v29, 0xbfb8aa3b, v20
	v_mul_f32_e32 v36, 0xbfb8aa3b, v33
	v_mul_f32_e32 v30, 0xbfb8aa3b, v34
	v_add_f32_e32 v8, v31, v8
	v_exp_f32_e32 v29, v29
	v_exp_f32_e32 v36, v36
	v_exp_f32_e32 v30, v30
	v_add_f32_dpp v8, v8, v8 quad_perm:[1,0,3,2] row_mask:0xf bank_mask:0xf bound_ctrl:1
	v_lshlrev_b32_e32 v35, 16, v23
	v_and_b32_e32 v23, 0xffff0000, v23
	v_add_f32_dpp v8, v8, v8 quad_perm:[2,3,0,1] row_mask:0xf bank_mask:0xf bound_ctrl:1
	v_and_b32_e32 v22, 0xffff0000, v22
	v_mul_f32_e32 v38, 0xbfb8aa3b, v22
	v_add_f32_dpp v8, v8, v8 row_half_mirror row_mask:0xf bank_mask:0xf bound_ctrl:1
	v_mul_f32_e32 v39, 0xbfb8aa3b, v35
	v_mul_f32_e32 v40, 0xbfb8aa3b, v23
	v_add_f32_dpp v8, v8, v8 row_mirror row_mask:0xf bank_mask:0xf bound_ctrl:1
	v_exp_f32_e32 v31, v38
	v_exp_f32_e32 v38, v39
	v_exp_f32_e32 v39, v40
	v_add_f32_e32 v29, 1.0, v29
	v_add_f32_e32 v36, 1.0, v36
	v_add_f32_e32 v40, 1.0, v30
	v_fmamk_f32 v8, v8, 0x3c000000, v15
	v_and_b32_e32 v21, 0xffff0000, v21
	v_rcp_f32_e32 v30, v29
	v_rcp_f32_e32 v29, v36
	v_rcp_f32_e32 v36, v40
	v_mul_f32_e32 v40, 0x4b800000, v8
	v_cmp_gt_f32_e32 vcc, s15, v8
	v_mul_f32_e32 v28, 0xbfb8aa3b, v32
	v_mul_f32_e32 v37, 0xbfb8aa3b, v21
	v_cndmask_b32_e32 v8, v8, v40, vcc
	v_exp_f32_e32 v28, v28
	v_exp_f32_e32 v37, v37
	v_rsq_f32_e32 v8, v8
	v_add_f32_e32 v41, 1.0, v31
	v_add_f32_e32 v28, 1.0, v28
	v_add_f32_e32 v37, 1.0, v37
	v_add_f32_e32 v42, 1.0, v38
	v_add_f32_e32 v39, 1.0, v39
	v_mul_f32_e32 v40, 0x45800000, v8
	v_rcp_f32_e32 v28, v28
	v_rcp_f32_e32 v31, v37
	v_rcp_f32_e32 v38, v41
	v_rcp_f32_e32 v37, v42
	v_rcp_f32_e32 v39, v39
	v_cndmask_b32_e32 v8, v8, v40, vcc
	v_pk_mul_f32 v[24:25], v[8:9], v[24:25] op_sel_hi:[0,1]
	v_pk_mul_f32 v[16:17], v[8:9], v[16:17] op_sel_hi:[0,1]
	v_pk_mul_f32 v[26:27], v[8:9], v[26:27] op_sel_hi:[0,1]
	v_pk_mul_f32 v[18:19], v[8:9], v[18:19] op_sel_hi:[0,1]
	v_pk_mul_f32 v[24:25], v[0:1], v[24:25]
	v_pk_mul_f32 v[16:17], v[12:13], v[16:17]
	v_pk_mul_f32 v[26:27], v[4:5], v[26:27]
	v_pk_mul_f32 v[18:19], v[2:3], v[18:19]
	v_pk_mul_f32 v[24:25], v[24:25], v[32:33]
	v_pk_mul_f32 v[16:17], v[16:17], v[20:21]
	v_pk_mul_f32 v[20:21], v[26:27], v[34:35]
	v_pk_mul_f32 v[18:19], v[18:19], v[22:23]
	v_pk_mul_f32 v[22:23], v[28:29], v[24:25]
	v_pk_mul_f32 v[20:21], v[36:37], v[20:21]
	v_pk_mul_f32 v[18:19], v[38:39], v[18:19]
	v_pk_mul_f32 v[16:17], v[30:31], v[16:17]
	v_bfe_u32 v8, v19, 16, 1
	v_bfe_u32 v27, v22, 16, 1
	v_bfe_u32 v28, v23, 16, 1
	v_bfe_u32 v29, v20, 16, 1
	v_bfe_u32 v30, v21, 16, 1
	v_bfe_u32 v24, v18, 16, 1
	v_bfe_u32 v25, v17, 16, 1
	v_bfe_u32 v26, v16, 16, 1
	v_add3_u32 v8, v19, v8, s6
	v_add3_u32 v19, v21, v30, s6
	v_add3_u32 v20, v20, v29, s6
	v_add3_u32 v21, v23, v28, s6
	v_add3_u32 v22, v22, v27, s6
	v_add3_u32 v16, v16, v26, s6
	v_add3_u32 v17, v17, v25, s6
	v_add3_u32 v18, v18, v24, s6
	v_lshrrev_b32_e32 v22, 16, v22
	v_lshrrev_b32_e32 v21, 16, v21
	v_lshrrev_b32_e32 v20, 16, v20
	v_lshrrev_b32_e32 v19, 16, v19
	v_and_or_b32 v19, v8, s9, v19
	v_and_or_b32 v18, v18, s9, v20
	v_and_or_b32 v17, v17, s9, v21
	v_and_or_b32 v16, v16, s9, v22
	global_store_dwordx4 v[6:7], v[16:19], off offset:2048
	s_ashr_i32 s4, s3, 1
	s_ashr_i32 s5, s4, 31
	s_mul_hi_i32 s16, s4, 0x3000
	s_mul_i32 s17, s4, 0x3000
	s_lshl_b64 s[4:5], s[4:5], 11
	v_and_or_b32 v6, s14, 4, v14
	s_add_u32 s4, s11, s4
	v_lshlrev_b32_e32 v8, 8, v6
	s_addc_u32 s5, s12, s5
	v_lshl_add_u64 v[6:7], s[4:5], 0, v[8:9]
	s_add_u32 s4, s7, s17
	v_lshl_add_u64 v[6:7], v[6:7], 0, v[10:11]
	s_addc_u32 s5, s10, s16
	global_load_dwordx4 v[68:71], v[6:7], off nt
	v_lshl_add_u64 v[6:7], s[4:5], 0, v[8:9]
	v_lshl_add_u64 v[6:7], v[6:7], 0, v[10:11]
	v_add_co_u32_e32 v20, vcc, s8, v6
	s_add_i32 s3, s3, s42
	s_nop 0
	v_addc_co_u32_e32 v21, vcc, 0, v7, vcc
	v_mov_b32_e32 v82, v6
	v_mov_b32_e32 v83, v7
	global_load_dwordx4 v[72:75], v[20:21], off offset:2048 nt
	s_add_i32 s14, s14, s13
	s_add_i32 s98, s98, 1
	s_cmp_lt_u32 s98, 4
	s_cbranch_scc1 .Lp4_trip
	s_nop 0
